# grid barrier: the leader that bumps the global generation word no longer waits for that atomic's completion (vmcnt(1) instead of vmcnt(0) at the two waits after it)
# baseline (speedup 1.0000x reference)
.LBB0_218:
	s_or_b64 exec, exec, s[4:5]
	s_mov_b64 s[4:5], exec
	v_mbcnt_lo_u32_b32 v0, s4, 0
	v_mbcnt_hi_u32_b32 v0, s5, v0
	v_cmp_eq_u32_e32 vcc, 0, v0
	s_waitcnt vmcnt(1)
	buffer_inv sc1
	s_and_saveexec_b64 s[6:7], vcc
	s_cbranch_execz .LBB0_220
	s_bcnt1_i32_b64 s4, s[4:5]
	v_mov_b32_e32 v0, s4
	v_readlane_b32 s4, v252, 54
	v_readlane_b32 s5, v252, 55
	s_nop 4
	s_nop 0
.LBB0_220:
	s_or_b64 exec, exec, s[6:7]
	s_waitcnt vmcnt(1)
.LBB0_221:
	s_or_b64 exec, exec, s[2:3]
	s_waitcnt lgkmcnt(0)
	s_barrier

.LBB0_411:
	s_or_b64 exec, exec, s[6:7]
	s_waitcnt vmcnt(1)
.LBB0_412:
	s_or_b64 exec, exec, s[2:3]
	s_waitcnt lgkmcnt(0)
	s_barrier

.LBB0_512:
	s_or_b64 exec, exec, s[6:7]
	s_waitcnt vmcnt(1)
.LBB0_513:
	s_or_b64 exec, exec, s[2:3]
	s_waitcnt lgkmcnt(0)
	s_barrier

.LBB0_622:
	s_or_b64 exec, exec, s[6:7]
	s_waitcnt vmcnt(1)
.LBB0_623:
	s_or_b64 exec, exec, s[2:3]
	s_waitcnt lgkmcnt(0)
	s_barrier

.LBB0_978:
	s_or_b64 exec, exec, s[6:7]
	s_waitcnt vmcnt(1)
.LBB0_979:
	s_or_b64 exec, exec, s[2:3]
	s_waitcnt lgkmcnt(0)
	s_barrier

.LBB0_1083:
	s_or_b64 exec, exec, s[6:7]
	s_waitcnt vmcnt(1)
.LBB0_1084:
	s_or_b64 exec, exec, s[2:3]
	s_waitcnt lgkmcnt(0)
	s_barrier

.LBB0_1156:
	s_or_b64 exec, exec, s[6:7]
	s_waitcnt vmcnt(1)
.LBB0_1157:
	s_or_b64 exec, exec, s[2:3]
	s_waitcnt lgkmcnt(0)
	s_barrier

.LBB0_1300:
	s_or_b64 exec, exec, s[6:7]
	s_waitcnt vmcnt(1)
.LBB0_1301:
	s_or_b64 exec, exec, s[2:3]
	s_waitcnt lgkmcnt(0)
	s_barrier

.LBB0_1371:
	s_or_b64 exec, exec, s[4:5]
	s_mov_b64 s[4:5], exec
	v_mbcnt_lo_u32_b32 v0, s4, 0
	v_mbcnt_hi_u32_b32 v0, s5, v0
	v_cmp_eq_u32_e32 vcc, 0, v0
	s_waitcnt vmcnt(1)
	buffer_inv sc1
	s_and_saveexec_b64 s[8:9], vcc
	s_cbranch_execz .LBB0_1373
	s_bcnt1_i32_b64 s4, s[4:5]
	v_mov_b32_e32 v0, s4
	v_readlane_b32 s4, v252, 54
	v_readlane_b32 s5, v252, 55
	s_nop 4
	s_nop 0
.LBB0_1373:
	s_or_b64 exec, exec, s[8:9]
	s_waitcnt vmcnt(1)
